# P5: odd waves run conv before their S5 pass-1 item (overlap latency-bound scan with bandwidth-bound conv)
# baseline (speedup 1.0000x reference)
.LBB0_955:
	s_or_b64 exec, exec, s[30:31]
	v_readlane_b32 s0, v251, 10
	s_mulk_i32 s0, 0x3200
	s_add_i32 s30, s0, 0
	s_add_u32 s54, s46, 0x17294000
	s_addc_u32 s55, s47, 0
	v_readlane_b32 s0, v251, 19
	v_readlane_b32 s36, v252, 0
	s_cmpk_gt_i32 s0, 0x6ff
	s_mov_b32 s1, 0
	v_readlane_b32 s46, v252, 10
	v_readlane_b32 s47, v252, 11
	s_waitcnt lgkmcnt(0)
	s_barrier
	v_writelane_b32 v253, s1, 0
.Lp5_top:
	v_readlane_b32 s37, v252, 1
	v_readlane_b32 s38, v252, 2
	v_readlane_b32 s39, v252, 3
	v_readlane_b32 s40, v252, 4
	v_readlane_b32 s41, v252, 5
	v_readlane_b32 s42, v252, 6
	v_readlane_b32 s43, v252, 7
	v_readlane_b32 s44, v252, 8
	v_readlane_b32 s45, v252, 9
	v_readlane_b32 s48, v252, 12
	v_readlane_b32 s49, v252, 13
	v_readlane_b32 s50, v252, 14
	v_readlane_b32 s51, v252, 15
	s_cbranch_scc1 .LBB0_980
	v_readlane_b32 s0, v253, 0
	s_cmp_eq_u32 s0, 0
	s_cbranch_scc0 .Lp5_s5
	v_readlane_b32 s0, v251, 19
	s_bitcmp1_b32 s0, 0
	s_cbranch_scc0 .Lp5_s5
	s_mov_b32 s0, 1
	s_nop 1
	v_writelane_b32 v253, s0, 0
	s_branch .LBB0_980
.Lp5_s5:
	v_mov_b32_e32 v41, 0
	s_movk_i32 s4, 0x2600
	v_readlane_b32 s5, v251, 19
	s_branch .LBB0_958

.Lp5_s5done:
	v_readlane_b32 s0, v253, 0
	s_cmp_eq_u32 s0, 0
	s_cbranch_scc1 .LBB0_980
	v_readlane_b32 s42, v251, 6
	v_readlane_b32 s43, v251, 7
	s_add_u32 s36, s42, 0x10f94000
	s_addc_u32 s37, s43, 0
	v_readlane_b32 s38, v251, 2
	v_readlane_b32 s39, v251, 3
	v_readlane_b32 s40, v251, 4
	v_readlane_b32 s41, v251, 5
	s_branch .Lp5_join

.LBB0_1022:
	v_writelane_b32 v251, s30, 49
	s_or_b64 exec, exec, s[0:1]
	v_readlane_b32 s0, v253, 0
	s_cmp_eq_u32 s0, 1
	s_cbranch_scc0 .Lp5_join
	s_mov_b32 s0, 2
	s_nop 1
	v_writelane_b32 v253, s0, 0
	s_mov_b32 s1, 0
	s_cmp_eq_u32 s1, 1
	s_branch .Lp5_top
.Lp5_join:
	s_mov_b64 s[34:35], s[72:73]
	s_mov_b32 s33, s68
	s_waitcnt vmcnt(0)
	s_barrier
	s_and_saveexec_b64 s[30:31], s[64:65]
	s_cbranch_execz .LBB0_1066
	s_add_i32 s0, 0, 0x26a10
	v_mov_b32_e32 v0, s0
	s_waitcnt vmcnt(0) expcnt(0) lgkmcnt(0)
	ds_read_b32 v2, v0
	s_add_i32 s0, 0, 0x26a14
	v_mov_b32_e32 v0, s0
	ds_read_b32 v0, v0
	s_waitcnt lgkmcnt(1)
	v_cmp_ne_u32_e32 vcc, 0, v2
	s_cbranch_vccnz .LBB0_1037
	s_add_u32 s2, s34, 0x1000
	s_addc_u32 s3, s35, 0
	s_add_u32 s4, s34, 0x1100
	s_addc_u32 s5, s35, 0
	s_add_u32 s6, s34, 0x1200
	s_addc_u32 s7, s35, 0
	s_add_u32 s8, s34, 0x1300
	s_addc_u32 s9, s35, 0
	s_mov_b32 s18, 1
	s_mov_b64 s[0:1], 0
	s_waitcnt lgkmcnt(0)
	v_mov_b64_e32 v[0:1], s[34:35]
	v_mov_b64_e32 v[2:3], s[2:3]
	v_mov_b64_e32 v[4:5], s[4:5]
	v_mov_b64_e32 v[6:7], s[6:7]
	v_mov_b64_e32 v[8:9], s[8:9]
	s_branch .LBB0_1027
